# v35 + nt stores for the layer-1 FFN bf16 weights (consumed >1ms later) in the prologue
# speedup vs baseline: 1.0046x; 1.0046x over previous
.LBB0_27:
	s_waitcnt lgkmcnt(3)
	v_cvt_pk_bf16_f32 v10, v10, v11
	s_waitcnt lgkmcnt(2)
	v_cvt_pk_bf16_f32 v11, v12, v13
	s_waitcnt lgkmcnt(1)
	v_cvt_pk_bf16_f32 v12, v14, v15
	v_ashrrev_i32_e32 v14, 31, v18
	s_waitcnt lgkmcnt(0)
	v_cvt_pk_bf16_f32 v13, v16, v17
	v_mul_lo_u32 v16, s65, v18
	v_mul_lo_u32 v17, s64, v14
	v_mad_u64_u32 v[14:15], s[4:5], s64, v18, 0
	v_add3_u32 v15, v15, v17, v16
	v_lshl_add_u64 v[8:9], v[14:15], 1, v[8:9]
	s_cmp_lt_u32 s81, 0x1080
	s_cbranch_scc1 .Lws7_def
	s_cmp_gt_u32 s81, 0x20ff
	s_cbranch_scc1 .Lws7_def
	global_store_dwordx4 v[8:9], v[10:13], off nt
	s_branch .Lws7_done
.Lws7_def:
	global_store_dwordx4 v[8:9], v[10:13], off
.Lws7_done:
	s_waitcnt lgkmcnt(0)
	s_add_i32 s81, s81, s38
	s_cmpk_gt_i32 s81, 0x25ef
	s_cbranch_scc1 .LBB0_115

.LBB0_61:
	s_lshl_b64 s[6:7], s[6:7], 1
	s_add_u32 s4, s4, s6
	s_addc_u32 s5, s5, s7
	s_waitcnt lgkmcnt(0)
	v_cvt_pk_bf16_f32 v10, v10, v11
	v_cvt_pk_bf16_f32 v11, v12, v13
	v_cvt_pk_bf16_f32 v12, v14, v15
	v_ashrrev_i32_e32 v14, 31, v19
	v_lshl_add_u64 v[8:9], s[4:5], 0, v[2:3]
	v_cvt_pk_bf16_f32 v13, v16, v17
	v_mul_lo_u32 v16, s65, v19
	v_mul_lo_u32 v17, s64, v14
	v_mad_u64_u32 v[14:15], s[4:5], s64, v19, 0
	v_add3_u32 v15, v15, v17, v16
	v_lshl_add_u64 v[14:15], v[14:15], 1, v[8:9]
	s_cmp_lt_u32 s81, 0x1080
	s_cbranch_scc1 .Lws6_def
	s_cmp_gt_u32 s81, 0x20ff
	s_cbranch_scc1 .Lws6_def
	global_store_dwordx4 v[14:15], v[10:13], off nt
	s_branch .Lws6_done
.Lws6_def:
	global_store_dwordx4 v[14:15], v[10:13], off
.Lws6_done:
	ds_read2_b32 v[10:11], v80 offset0:8 offset1:73
	ds_read2_b32 v[12:13], v80 offset0:138 offset1:203
	ds_read2_b32 v[14:15], v18 offset0:12 offset1:77
	ds_read2_b32 v[16:17], v18 offset0:142 offset1:207
	v_cndmask_b32_e64 v20, 0, 1, s[68:69]
	v_cmp_ne_u32_e64 s[6:7], 1, v20
	v_cndmask_b32_e64 v20, 0, 1, s[70:71]
	v_or_b32_e32 v19, s66, v81
	s_andn2_b64 vcc, exec, s[68:69]
	v_cmp_ne_u32_e64 s[4:5], 1, v20
	s_cbranch_vccnz .LBB0_67
	s_and_b64 vcc, exec, s[4:5]
	s_mov_b64 s[68:69], -1
	s_cbranch_vccnz .LBB0_64
	v_or_b32_e32 v20, s67, v81
	s_mov_b64 s[68:69], 0

.LBB0_67:
	s_waitcnt lgkmcnt(3)
	v_cvt_pk_bf16_f32 v20, v10, v11
	v_ashrrev_i32_e32 v10, 31, v19
	v_mul_lo_u32 v11, s65, v19
	v_mul_lo_u32 v10, s64, v10
	v_mad_u64_u32 v[24:25], s[26:27], s64, v19, 0
	s_waitcnt lgkmcnt(2)
	v_cvt_pk_bf16_f32 v21, v12, v13
	s_waitcnt lgkmcnt(1)
	v_cvt_pk_bf16_f32 v22, v14, v15
	s_waitcnt lgkmcnt(0)
	v_cvt_pk_bf16_f32 v23, v16, v17
	v_add3_u32 v25, v25, v10, v11
	ds_read2_b32 v[10:11], v80 offset0:16 offset1:81
	ds_read2_b32 v[12:13], v80 offset0:146 offset1:211
	ds_read2_b32 v[14:15], v18 offset0:20 offset1:85
	ds_read2_b32 v[16:17], v18 offset0:150 offset1:215
	v_lshl_add_u64 v[24:25], v[24:25], 1, v[8:9]
	s_and_b64 vcc, exec, s[6:7]
	v_or_b32_e32 v19, s66, v82
	s_cmp_lt_u32 s81, 0x1080
	s_cbranch_scc1 .Lws5_def
	s_cmp_gt_u32 s81, 0x20ff
	s_cbranch_scc1 .Lws5_def
	global_store_dwordx4 v[24:25], v[20:23], off nt
	s_branch .Lws5_done
.Lws5_def:
	global_store_dwordx4 v[24:25], v[20:23], off
.Lws5_done:
	s_cbranch_vccnz .LBB0_73
	s_and_b64 vcc, exec, s[4:5]
	s_mov_b64 s[68:69], -1
	s_cbranch_vccnz .LBB0_70
	v_or_b32_e32 v20, s67, v82
	s_mov_b64 s[68:69], 0

.LBB0_73:
	s_waitcnt lgkmcnt(3)
	v_cvt_pk_bf16_f32 v20, v10, v11
	v_ashrrev_i32_e32 v10, 31, v19
	v_mul_lo_u32 v11, s65, v19
	v_mul_lo_u32 v10, s64, v10
	v_mad_u64_u32 v[24:25], s[26:27], s64, v19, 0
	s_waitcnt lgkmcnt(2)
	v_cvt_pk_bf16_f32 v21, v12, v13
	s_waitcnt lgkmcnt(1)
	v_cvt_pk_bf16_f32 v22, v14, v15
	s_waitcnt lgkmcnt(0)
	v_cvt_pk_bf16_f32 v23, v16, v17
	v_add3_u32 v25, v25, v10, v11
	ds_read2_b32 v[10:11], v80 offset0:24 offset1:89
	ds_read2_b32 v[12:13], v80 offset0:154 offset1:219
	ds_read2_b32 v[14:15], v18 offset0:28 offset1:93
	ds_read2_b32 v[16:17], v18 offset0:158 offset1:223
	v_lshl_add_u64 v[24:25], v[24:25], 1, v[8:9]
	s_and_b64 vcc, exec, s[6:7]
	v_or_b32_e32 v19, s66, v83
	s_cmp_lt_u32 s81, 0x1080
	s_cbranch_scc1 .Lws4_def
	s_cmp_gt_u32 s81, 0x20ff
	s_cbranch_scc1 .Lws4_def
	global_store_dwordx4 v[24:25], v[20:23], off nt
	s_branch .Lws4_done

.Lws4_done:
	s_cbranch_vccnz .LBB0_79
	s_and_b64 vcc, exec, s[4:5]
	s_mov_b64 s[68:69], -1
	s_cbranch_vccnz .LBB0_76
	v_or_b32_e32 v20, s67, v83
	s_mov_b64 s[68:69], 0

.LBB0_79:
	s_waitcnt lgkmcnt(3)
	v_cvt_pk_bf16_f32 v20, v10, v11
	v_ashrrev_i32_e32 v10, 31, v19
	v_mul_lo_u32 v11, s65, v19
	v_mul_lo_u32 v10, s64, v10
	v_mad_u64_u32 v[24:25], s[26:27], s64, v19, 0
	s_waitcnt lgkmcnt(2)
	v_cvt_pk_bf16_f32 v21, v12, v13
	s_waitcnt lgkmcnt(1)
	v_cvt_pk_bf16_f32 v22, v14, v15
	s_waitcnt lgkmcnt(0)
	v_cvt_pk_bf16_f32 v23, v16, v17
	v_add3_u32 v25, v25, v10, v11
	ds_read2_b32 v[10:11], v80 offset0:32 offset1:97
	ds_read2_b32 v[12:13], v80 offset0:162 offset1:227
	ds_read2_b32 v[14:15], v18 offset0:36 offset1:101
	ds_read2_b32 v[16:17], v18 offset0:166 offset1:231
	v_lshl_add_u64 v[24:25], v[24:25], 1, v[8:9]
	s_and_b64 vcc, exec, s[6:7]
	v_or_b32_e32 v19, s66, v84
	s_cmp_lt_u32 s81, 0x1080
	s_cbranch_scc1 .Lws3_def
	s_cmp_gt_u32 s81, 0x20ff
	s_cbranch_scc1 .Lws3_def
	global_store_dwordx4 v[24:25], v[20:23], off nt
	s_branch .Lws3_done

.Lws3_done:
	s_cbranch_vccnz .LBB0_85
	s_and_b64 vcc, exec, s[4:5]
	s_mov_b64 s[68:69], -1
	s_cbranch_vccnz .LBB0_82
	v_or_b32_e32 v20, s67, v84
	s_mov_b64 s[68:69], 0

.LBB0_85:
	s_waitcnt lgkmcnt(3)
	v_cvt_pk_bf16_f32 v20, v10, v11
	v_ashrrev_i32_e32 v10, 31, v19
	v_mul_lo_u32 v11, s65, v19
	v_mul_lo_u32 v10, s64, v10
	v_mad_u64_u32 v[24:25], s[26:27], s64, v19, 0
	s_waitcnt lgkmcnt(2)
	v_cvt_pk_bf16_f32 v21, v12, v13
	s_waitcnt lgkmcnt(1)
	v_cvt_pk_bf16_f32 v22, v14, v15
	s_waitcnt lgkmcnt(0)
	v_cvt_pk_bf16_f32 v23, v16, v17
	v_add3_u32 v25, v25, v10, v11
	ds_read2_b32 v[10:11], v80 offset0:40 offset1:105
	ds_read2_b32 v[12:13], v80 offset0:170 offset1:235
	ds_read2_b32 v[14:15], v18 offset0:44 offset1:109
	ds_read2_b32 v[16:17], v18 offset0:174 offset1:239
	v_lshl_add_u64 v[24:25], v[24:25], 1, v[8:9]
	s_and_b64 vcc, exec, s[6:7]
	v_or_b32_e32 v19, s66, v85
	s_cmp_lt_u32 s81, 0x1080
	s_cbranch_scc1 .Lws2_def
	s_cmp_gt_u32 s81, 0x20ff
	s_cbranch_scc1 .Lws2_def
	global_store_dwordx4 v[24:25], v[20:23], off nt
	s_branch .Lws2_done

.Lws2_done:
	s_cbranch_vccnz .LBB0_91
	s_and_b64 vcc, exec, s[4:5]
	s_mov_b64 s[68:69], -1
	s_cbranch_vccnz .LBB0_88
	v_or_b32_e32 v20, s67, v85
	s_mov_b64 s[68:69], 0

.LBB0_91:
	s_waitcnt lgkmcnt(3)
	v_cvt_pk_bf16_f32 v20, v10, v11
	v_ashrrev_i32_e32 v10, 31, v19
	v_mul_lo_u32 v11, s65, v19
	v_mul_lo_u32 v10, s64, v10
	v_mad_u64_u32 v[24:25], s[26:27], s64, v19, 0
	s_waitcnt lgkmcnt(2)
	v_cvt_pk_bf16_f32 v21, v12, v13
	s_waitcnt lgkmcnt(1)
	v_cvt_pk_bf16_f32 v22, v14, v15
	s_waitcnt lgkmcnt(0)
	v_cvt_pk_bf16_f32 v23, v16, v17
	v_add3_u32 v25, v25, v10, v11
	ds_read2_b32 v[10:11], v80 offset0:48 offset1:113
	ds_read2_b32 v[12:13], v80 offset0:178 offset1:243
	ds_read2_b32 v[14:15], v18 offset0:52 offset1:117
	ds_read2_b32 v[16:17], v18 offset0:182 offset1:247
	v_lshl_add_u64 v[24:25], v[24:25], 1, v[8:9]
	s_and_b64 vcc, exec, s[6:7]
	v_or_b32_e32 v19, s66, v86
	s_cmp_lt_u32 s81, 0x1080
	s_cbranch_scc1 .Lws1_def
	s_cmp_gt_u32 s81, 0x20ff
	s_cbranch_scc1 .Lws1_def
	global_store_dwordx4 v[24:25], v[20:23], off nt
	s_branch .Lws1_done

.Lws1_done:
	s_cbranch_vccnz .LBB0_97
	s_and_b64 vcc, exec, s[4:5]
	s_mov_b64 s[68:69], -1
	s_cbranch_vccnz .LBB0_94
	v_or_b32_e32 v20, s67, v86
	s_mov_b64 s[68:69], 0

.LBB0_97:
	s_waitcnt lgkmcnt(3)
	v_cvt_pk_bf16_f32 v20, v10, v11
	v_ashrrev_i32_e32 v10, 31, v19
	v_mul_lo_u32 v11, s65, v19
	v_mul_lo_u32 v10, s64, v10
	v_mad_u64_u32 v[24:25], s[26:27], s64, v19, 0
	s_waitcnt lgkmcnt(2)
	v_cvt_pk_bf16_f32 v21, v12, v13
	s_waitcnt lgkmcnt(1)
	v_cvt_pk_bf16_f32 v22, v14, v15
	s_waitcnt lgkmcnt(0)
	v_cvt_pk_bf16_f32 v23, v16, v17
	v_add3_u32 v25, v25, v10, v11
	ds_read2_b32 v[10:11], v80 offset0:56 offset1:121
	ds_read2_b32 v[12:13], v80 offset0:186 offset1:251
	ds_read2_b32 v[14:15], v18 offset0:60 offset1:125
	ds_read2_b32 v[16:17], v18 offset0:190 offset1:255
	v_lshl_add_u64 v[18:19], v[24:25], 1, v[8:9]
	s_cmp_lt_u32 s81, 0x1080
	s_cbranch_scc1 .Lws0_def
	s_cmp_gt_u32 s81, 0x20ff
	s_cbranch_scc1 .Lws0_def
	global_store_dwordx4 v[18:19], v[20:23], off nt
	s_branch .Lws0_done
.Lws0_def:
	global_store_dwordx4 v[18:19], v[20:23], off
.Lws0_done:
	s_and_b64 vcc, exec, s[6:7]
	v_or_b32_e32 v18, s66, v87
	s_cbranch_vccnz .LBB0_27
	s_and_b64 vcc, exec, s[4:5]
	s_mov_b64 s[4:5], -1
	s_cbranch_vccnz .LBB0_100
	v_or_b32_e32 v19, s67, v87
	s_mov_b64 s[4:5], 0
